# all load-segment micro-trims together (merged waits + dead m0 writes removed in every GEMM loop)
# baseline (speedup 1.0000x reference)
; #define PG8_STAGE(bufoff, gbase, voff) do { _Pragma("unroll") for (int _i = 0; _i < 2; ++_i) \
;         __builtin_amdgcn_global_load_lds((const unsigned*)((const char*)(gbase) + (voff)[_i]), (PG8_LAS unsigned*)(lds + (bufoff) + ldsw + _i * 8192), 16, 0, 0); } while (0)
; #define PG8_LDA(dst, b, h) do { _Pragma("unroll") for (int m = 0; m < 4; ++m) _Pragma("unroll") for (int k = 0; k < 2; ++k) dst[m][k] = *(const PG8_LAS bf16x8*)(lds + PG8_SA(b, h) + aoff + m * 2048 + k * 1024); } while (0)
; #define PG8_LDB(dst, b, h) do { _Pragma("unroll") for (int n = 0; n < 2; ++n) _Pragma("unroll") for (int k = 0; k < 2; ++k) dst[n][k] = *(const PG8_LAS bf16x8*)(lds + PG8_SB(b, h) + boff + n * 2048 + k * 1024); } while (0)
; #define PG8_MMA(ai, bj, At, Bt) do { __builtin_amdgcn_s_setprio(1); _Pragma("unroll") for (int m = 0; m < 4; ++m) _Pragma("unroll") for (int n = 0; n < 2; ++n) _Pragma("unroll") for (int k = 0; k < 2; ++k) \
;         acc[ai][bj][m][n] = __builtin_amdgcn_mfma_f32_16x16x32_bf16(Bt[n][k], At[m][k], acc[ai][bj][m][n], 0, 0, 0); __builtin_amdgcn_s_setprio(0); } while (0)
; #define PG8_WAIT_V(n) asm volatile("s_waitcnt vmcnt(" #n ")" ::: "memory")
; template <class Epi, class Sched, bool ALIGN_EPI = false, bool SP2 = false>
; __device__ __forceinline__ void gemm_phase(PG8_LAS unsigned char* lds, const Gemm g, const Sched& S, const Epi& E) {
;     ...
;             PG8_LDB(B0, 0, 0); PG8_LDB(B1, 0, 1); PG8_SCHED; PG8_LDA(At, 0, 0); PG8_STAGE(PG8_SA(1, 1), a1 + hstepA, voffA);
;             PG8_WAIT_V(8); PG8_WAIT_L(0); PG8_BAR; PG8_MMA(0, 0, At, B0); PG8_MMA(0, 1, At, B1); PG8_BAR; PG8_SCHED;
;             PG8_LDA(At, 0, 1); PG8_STAGE(PG8_SB(0, 0), b2, voffB); PG8_STAGE(PG8_SB(0, 1), b2 + hstepB, voffB); PG8_STAGE(PG8_SA(0, 0), a2, voffA);
;             PG8_WAIT_V(8); PG8_WAIT_L(0); PG8_BAR; PG8_MMA(1, 0, At, B0); PG8_MMA(1, 1, At, B1); PG8_BAR; PG8_SCHED;
;             PG8_LDB(B0, 1, 0); PG8_LDB(B1, 1, 1); PG8_SCHED; PG8_LDA(At, 1, 0); PG8_STAGE(PG8_SA(0, 1), a2 + hstepA, voffA);
;             PG8_WAIT_V(8); PG8_WAIT_L(0); PG8_BAR; PG8_MMA(0, 0, At, B0); PG8_MMA(0, 1, At, B1); PG8_BAR; PG8_SCHED;
;             PG8_LDA(At, 1, 1); PG8_STAGE(PG8_SB(1, 0), b3, voffB); PG8_STAGE(PG8_SB(1, 1), b3 + hstepB, voffB); PG8_STAGE(PG8_SA(1, 0), a3, voffA);
;             PG8_WAIT_V(8); PG8_WAIT_L(0); PG8_BAR; PG8_MMA(1, 0, At, B0); PG8_MMA(1, 1, At, B1); PG8_BAR; PG8_SCHED;
.LBB0_1217:
	v_add_u32_e32 v1, s57, v154
	ds_read_b128 v[158:161], v1
	ds_read_b128 v[162:165], v1 offset:1024
	ds_read_b128 v[166:169], v1 offset:2048
	ds_read_b128 v[170:173], v1 offset:3072
	v_add_u32_e32 v1, s58, v154
	s_add_u32 s42, s78, s18
	ds_read_b128 v[174:177], v1
	ds_read_b128 v[178:181], v1 offset:1024
	ds_read_b128 v[182:185], v1 offset:2048
	ds_read_b128 v[186:189], v1 offset:3072
	s_addc_u32 s43, s79, s19
	s_add_u32 s42, s42, 0x100
	s_addc_u32 s43, s43, 0
	s_add_u32 s69, s66, s18
	s_addc_u32 s70, s67, s19
	s_cmpk_eq_i32 s18, 0xf00
	s_cselect_b32 s43, s62, s43
	s_cselect_b32 s42, s63, s42
	s_cselect_b32 vcc_hi, s51, s70
	s_cselect_b32 vcc_lo, s65, s69
	v_lshl_add_u64 v[2:3], v[148:149], 0, s[18:19]
	ds_read_b128 v[190:193], v156
	ds_read_b128 v[194:197], v156 offset:1024
	ds_read_b128 v[198:201], v156 offset:2048
	ds_read_b128 v[202:205], v156 offset:3072
	ds_read_b128 v[206:209], v156 offset:4096
	ds_read_b128 v[210:213], v156 offset:5120
	ds_read_b128 v[214:217], v156 offset:6144
	ds_read_b128 v[218:221], v156 offset:7168
	s_add_u32 s98, s78, s18
	s_addc_u32 s99, s79, s19
	s_add_u32 s98, s98, 0x80
	s_addc_u32 s99, s99, 0
	s_mov_b32 m0, s47
	s_nop 0
	global_load_lds_dwordx4 v132, s[98:99]
	s_mov_b32 m0, s56
	s_nop 0
	global_load_lds_dwordx4 v136, s[98:99]
	s_add_i32 m0, s5, 0xc000
	s_nop 0
	global_load_lds_dwordx4 v[2:3], off
	v_lshl_add_u64 v[2:3], v[150:151], 0, s[18:19]
	s_add_i32 m0, s5, 0xe000
	s_nop 0
	global_load_lds_dwordx4 v[2:3], off
	s_waitcnt vmcnt(8) lgkmcnt(0)
	s_barrier
	s_setprio 1
	v_mfma_f32_16x16x32_bf16 v[128:131], v[158:161], v[190:193], v[128:131]
	v_mfma_f32_16x16x32_bf16 v[124:127], v[166:169], v[190:193], v[124:127]
	v_mfma_f32_16x16x32_bf16 v[112:115], v[158:161], v[198:201], v[112:115]
	v_mfma_f32_16x16x32_bf16 v[108:111], v[166:169], v[198:201], v[108:111]
	v_mfma_f32_16x16x32_bf16 v[96:99], v[158:161], v[206:209], v[96:99]
	v_mfma_f32_16x16x32_bf16 v[92:95], v[166:169], v[206:209], v[92:95]
	v_mfma_f32_16x16x32_bf16 v[80:83], v[158:161], v[214:217], v[80:83]
	v_mfma_f32_16x16x32_bf16 v[76:79], v[166:169], v[214:217], v[76:79]
	v_mfma_f32_16x16x32_bf16 v[128:131], v[162:165], v[194:197], v[128:131]
	v_mfma_f32_16x16x32_bf16 v[124:127], v[170:173], v[194:197], v[124:127]
	v_mfma_f32_16x16x32_bf16 v[112:115], v[162:165], v[202:205], v[112:115]
	v_mfma_f32_16x16x32_bf16 v[108:111], v[170:173], v[202:205], v[108:111]
	v_mfma_f32_16x16x32_bf16 v[96:99], v[162:165], v[210:213], v[96:99]
	v_mfma_f32_16x16x32_bf16 v[92:95], v[170:173], v[210:213], v[92:95]
	v_mfma_f32_16x16x32_bf16 v[80:83], v[162:165], v[218:221], v[80:83]
	v_mfma_f32_16x16x32_bf16 v[76:79], v[170:173], v[218:221], v[76:79]
	s_setprio 0
	s_setprio 1
	v_mfma_f32_16x16x32_bf16 v[120:123], v[174:177], v[190:193], v[120:123]
	v_mfma_f32_16x16x32_bf16 v[116:119], v[182:185], v[190:193], v[116:119]
	v_mfma_f32_16x16x32_bf16 v[104:107], v[174:177], v[198:201], v[104:107]
	v_mfma_f32_16x16x32_bf16 v[100:103], v[182:185], v[198:201], v[100:103]
	v_mfma_f32_16x16x32_bf16 v[88:91], v[174:177], v[206:209], v[88:91]
	v_mfma_f32_16x16x32_bf16 v[84:87], v[182:185], v[206:209], v[84:87]
	v_mfma_f32_16x16x32_bf16 v[72:75], v[174:177], v[214:217], v[72:75]
	v_mfma_f32_16x16x32_bf16 v[68:71], v[182:185], v[214:217], v[68:71]
	v_mfma_f32_16x16x32_bf16 v[120:123], v[178:181], v[194:197], v[120:123]
	v_mfma_f32_16x16x32_bf16 v[116:119], v[186:189], v[194:197], v[116:119]
	v_mfma_f32_16x16x32_bf16 v[104:107], v[178:181], v[202:205], v[104:107]
	v_mfma_f32_16x16x32_bf16 v[100:103], v[186:189], v[202:205], v[100:103]
	v_mfma_f32_16x16x32_bf16 v[88:91], v[178:181], v[210:213], v[88:91]
	v_mfma_f32_16x16x32_bf16 v[84:87], v[186:189], v[210:213], v[84:87]
	v_mfma_f32_16x16x32_bf16 v[72:75], v[178:181], v[218:221], v[72:75]
	v_mfma_f32_16x16x32_bf16 v[68:71], v[186:189], v[218:221], v[68:71]
	s_setprio 0
	s_barrier
	s_add_i32 s69, s57, s4
	s_mov_b32 m0, s69
	ds_read_b128 v[190:193], v156 offset:16384
	ds_read_b128 v[194:197], v156 offset:17408
	ds_read_b128 v[198:201], v156 offset:18432
	ds_read_b128 v[202:205], v156 offset:19456
	ds_read_b128 v[206:209], v156 offset:20480
	ds_read_b128 v[210:213], v156 offset:21504
	ds_read_b128 v[214:217], v156 offset:22528
	ds_read_b128 v[218:221], v156 offset:23552
	global_load_lds_dwordx4 v134, vcc
	s_add_i32 m0, s69, 0x2000
	s_add_u32 s70, vcc_lo, 0x80000
	s_addc_u32 s71, vcc_hi, 0
	s_add_i32 s69, s58, s4
	global_load_lds_dwordx4 v138, vcc
	s_mov_b32 m0, s69
	s_nop 0
	global_load_lds_dwordx4 v134, s[70:71]
	s_add_i32 m0, s69, 0x2000
	s_nop 0
	global_load_lds_dwordx4 v138, s[70:71]
	s_waitcnt vmcnt(6) lgkmcnt(0)
	s_barrier
; #define PG8_STAGE(bufoff, gbase, voff) do { _Pragma("unroll") for (int _i = 0; _i < 2; ++_i) \
;         __builtin_amdgcn_global_load_lds((const unsigned*)((const char*)(gbase) + (voff)[_i]), (PG8_LAS unsigned*)(lds + (bufoff) + ldsw + _i * 8192), 16, 0, 0); } while (0)
; #define PG8_LDA(dst, b, h) do { _Pragma("unroll") for (int m = 0; m < 4; ++m) _Pragma("unroll") for (int k = 0; k < 2; ++k) dst[m][k] = *(const PG8_LAS bf16x8*)(lds + PG8_SA(b, h) + aoff + m * 2048 + k * 1024); } while (0)
; #define PG8_LDB(dst, b, h) do { _Pragma("unroll") for (int n = 0; n < 2; ++n) _Pragma("unroll") for (int k = 0; k < 2; ++k) dst[n][k] = *(const PG8_LAS bf16x8*)(lds + PG8_SB(b, h) + boff + n * 2048 + k * 1024); } while (0)
; #define PG8_MMA(ai, bj, At, Bt) do { __builtin_amdgcn_s_setprio(1); _Pragma("unroll") for (int m = 0; m < 4; ++m) _Pragma("unroll") for (int n = 0; n < 2; ++n) _Pragma("unroll") for (int k = 0; k < 2; ++k) \
;         acc[ai][bj][m][n] = __builtin_amdgcn_mfma_f32_16x16x32_bf16(Bt[n][k], At[m][k], acc[ai][bj][m][n], 0, 0, 0); __builtin_amdgcn_s_setprio(0); } while (0)
; #define PG8_WAIT_V(n) asm volatile("s_waitcnt vmcnt(" #n ")" ::: "memory")
; #define PG8_WAIT_L(n) asm volatile("s_waitcnt lgkmcnt(" #n ")" ::: "memory")
; #define PG8_BAR __builtin_amdgcn_s_barrier()
; #define PG8_SCHED __builtin_amdgcn_sched_barrier(0)
; template <class Epi, class Sched, bool ALIGN_EPI = false, bool SP2 = false>
; __device__ __forceinline__ void gemm_phase(PG8_LAS unsigned char* lds, const Gemm g, const Sched& S, const Epi& E) {
;     ...
;             PG8_LDB(B0, 1, 0); PG8_LDB(B1, 1, 1); PG8_SCHED; PG8_LDA(At, 1, 0); PG8_STAGE(PG8_SA(0, 1), a2 + hstepA, voffA);
;             PG8_WAIT_V(8); PG8_WAIT_L(0); PG8_BAR; PG8_MMA(0, 0, At, B0); PG8_MMA(0, 1, At, B1); PG8_BAR; PG8_SCHED;
;             PG8_LDA(At, 1, 1); PG8_STAGE(PG8_SB(1, 0), b3, voffB); PG8_STAGE(PG8_SB(1, 1), b3 + hstepB, voffB); PG8_STAGE(PG8_SA(1, 0), a3, voffA);
;             PG8_WAIT_V(8); PG8_WAIT_L(0); PG8_BAR; PG8_MMA(1, 0, At, B0); PG8_MMA(1, 1, At, B1); PG8_BAR; PG8_SCHED;
	s_setprio 1
	v_mfma_f32_16x16x32_bf16 v[64:67], v[158:161], v[190:193], v[64:67]
	v_mfma_f32_16x16x32_bf16 v[60:63], v[166:169], v[190:193], v[60:63]
	v_mfma_f32_16x16x32_bf16 v[48:51], v[158:161], v[198:201], v[48:51]
	v_mfma_f32_16x16x32_bf16 v[44:47], v[166:169], v[198:201], v[44:47]
	v_mfma_f32_16x16x32_bf16 v[32:35], v[158:161], v[206:209], v[32:35]
	v_mfma_f32_16x16x32_bf16 v[28:31], v[166:169], v[206:209], v[28:31]
	v_mfma_f32_16x16x32_bf16 v[16:19], v[158:161], v[214:217], v[16:19]
	v_mfma_f32_16x16x32_bf16 v[12:15], v[166:169], v[214:217], v[12:15]
	v_mfma_f32_16x16x32_bf16 v[64:67], v[162:165], v[194:197], v[64:67]
	v_mfma_f32_16x16x32_bf16 v[60:63], v[170:173], v[194:197], v[60:63]
	v_mfma_f32_16x16x32_bf16 v[48:51], v[162:165], v[202:205], v[48:51]
	v_mfma_f32_16x16x32_bf16 v[44:47], v[170:173], v[202:205], v[44:47]
	v_mfma_f32_16x16x32_bf16 v[32:35], v[162:165], v[210:213], v[32:35]
	v_mfma_f32_16x16x32_bf16 v[28:31], v[170:173], v[210:213], v[28:31]
	v_mfma_f32_16x16x32_bf16 v[16:19], v[162:165], v[218:221], v[16:19]
	v_mfma_f32_16x16x32_bf16 v[12:15], v[170:173], v[218:221], v[12:15]
	s_setprio 0
	s_setprio 1
	v_mfma_f32_16x16x32_bf16 v[56:59], v[174:177], v[190:193], v[56:59]
	v_mfma_f32_16x16x32_bf16 v[52:55], v[182:185], v[190:193], v[52:55]
	v_mfma_f32_16x16x32_bf16 v[40:43], v[174:177], v[198:201], v[40:43]
	v_mfma_f32_16x16x32_bf16 v[36:39], v[182:185], v[198:201], v[36:39]
	v_mfma_f32_16x16x32_bf16 v[24:27], v[174:177], v[206:209], v[24:27]
	v_mfma_f32_16x16x32_bf16 v[20:23], v[182:185], v[206:209], v[20:23]
	v_mfma_f32_16x16x32_bf16 v[8:11], v[174:177], v[214:217], v[8:11]
	v_mfma_f32_16x16x32_bf16 v[2:5], v[182:185], v[214:217], v[4:7]
	v_mfma_f32_16x16x32_bf16 v[56:59], v[178:181], v[194:197], v[56:59]
	v_mfma_f32_16x16x32_bf16 v[52:55], v[186:189], v[194:197], v[52:55]
	v_mfma_f32_16x16x32_bf16 v[40:43], v[178:181], v[202:205], v[40:43]
	v_mfma_f32_16x16x32_bf16 v[36:39], v[186:189], v[202:205], v[36:39]
	v_mfma_f32_16x16x32_bf16 v[24:27], v[178:181], v[210:213], v[24:27]
	v_mfma_f32_16x16x32_bf16 v[20:23], v[186:189], v[210:213], v[20:23]
	v_mfma_f32_16x16x32_bf16 v[8:11], v[178:181], v[218:221], v[8:11]
	v_mfma_f32_16x16x32_bf16 v[2:5], v[186:189], v[218:221], v[2:5]
	s_setprio 0
	s_barrier
	s_add_i32 s69, 0, 0x18000
	v_add_u32_e32 v1, s69, v154
	s_add_i32 s70, 0, 0x1c000
	ds_read_b128 v[158:161], v1
	ds_read_b128 v[162:165], v1 offset:1024
	ds_read_b128 v[166:169], v1 offset:2048
	ds_read_b128 v[170:173], v1 offset:3072
	v_add_u32_e32 v1, s70, v154
	ds_read_b128 v[174:177], v1
	ds_read_b128 v[178:181], v1 offset:1024
	ds_read_b128 v[182:185], v1 offset:2048
	ds_read_b128 v[186:189], v1 offset:3072
	s_mov_b64 s[100:101], s[42:43]
	s_add_u32 s42, s42, 0x80000
	s_addc_u32 s43, s43, 0
	ds_read_b128 v[190:193], v156 offset:32768
	ds_read_b128 v[194:197], v156 offset:33792
	ds_read_b128 v[198:201], v156 offset:34816
	ds_read_b128 v[202:205], v156 offset:35840
	ds_read_b128 v[206:209], v156 offset:36864
	ds_read_b128 v[210:213], v156 offset:37888
	ds_read_b128 v[214:217], v156 offset:38912
	ds_read_b128 v[218:221], v156 offset:39936
	s_mov_b32 m0, s5
	s_nop 0
	global_load_lds_dwordx4 v132, s[100:101]
	s_mov_b32 m0, s6
	s_nop 0
	global_load_lds_dwordx4 v136, s[100:101]
	s_mov_b32 m0, s7
	s_nop 0
	global_load_lds_dwordx4 v132, s[42:43]
	s_mov_b32 m0, s33
	s_nop 0
	global_load_lds_dwordx4 v136, s[42:43]
	s_waitcnt vmcnt(8) lgkmcnt(0)
	s_barrier
; #define PG8_STAGE(bufoff, gbase, voff) do { _Pragma("unroll") for (int _i = 0; _i < 2; ++_i) \
;         __builtin_amdgcn_global_load_lds((const unsigned*)((const char*)(gbase) + (voff)[_i]), (PG8_LAS unsigned*)(lds + (bufoff) + ldsw + _i * 8192), 16, 0, 0); } while (0)
; #define PG8_LDA(dst, b, h) do { _Pragma("unroll") for (int m = 0; m < 4; ++m) _Pragma("unroll") for (int k = 0; k < 2; ++k) dst[m][k] = *(const PG8_LAS bf16x8*)(lds + PG8_SA(b, h) + aoff + m * 2048 + k * 1024); } while (0)
; #define PG8_LDB(dst, b, h) do { _Pragma("unroll") for (int n = 0; n < 2; ++n) _Pragma("unroll") for (int k = 0; k < 2; ++k) dst[n][k] = *(const PG8_LAS bf16x8*)(lds + PG8_SB(b, h) + boff + n * 2048 + k * 1024); } while (0)
; #define PG8_MMA(ai, bj, At, Bt) do { __builtin_amdgcn_s_setprio(1); _Pragma("unroll") for (int m = 0; m < 4; ++m) _Pragma("unroll") for (int n = 0; n < 2; ++n) _Pragma("unroll") for (int k = 0; k < 2; ++k) \
;         acc[ai][bj][m][n] = __builtin_amdgcn_mfma_f32_16x16x32_bf16(Bt[n][k], At[m][k], acc[ai][bj][m][n], 0, 0, 0); __builtin_amdgcn_s_setprio(0); } while (0)
; #define PG8_WAIT_V(n) asm volatile("s_waitcnt vmcnt(" #n ")" ::: "memory")
; #define PG8_WAIT_L(n) asm volatile("s_waitcnt lgkmcnt(" #n ")" ::: "memory")
; #define PG8_BAR __builtin_amdgcn_s_barrier()
; #define PG8_SCHED __builtin_amdgcn_sched_barrier(0)
; template <class Epi, class Sched, bool ALIGN_EPI = false, bool SP2 = false>
; __device__ __forceinline__ void gemm_phase(PG8_LAS unsigned char* lds, const Gemm g, const Sched& S, const Epi& E) {
;     ...
;         for (int t = 0; t < nt; t += 2) {
;     ...
;             PG8_LDB(B0, 1, 0); PG8_LDB(B1, 1, 1); PG8_SCHED; PG8_LDA(At, 1, 0); PG8_STAGE(PG8_SA(0, 1), a2 + hstepA, voffA);
;             PG8_WAIT_V(8); PG8_WAIT_L(0); PG8_BAR; PG8_MMA(0, 0, At, B0); PG8_MMA(0, 1, At, B1); PG8_BAR; PG8_SCHED;
;             PG8_LDA(At, 1, 1); PG8_STAGE(PG8_SB(1, 0), b3, voffB); PG8_STAGE(PG8_SB(1, 1), b3 + hstepB, voffB); PG8_STAGE(PG8_SA(1, 0), a3, voffA);
;             PG8_WAIT_V(8); PG8_WAIT_L(0); PG8_BAR; PG8_MMA(1, 0, At, B0); PG8_MMA(1, 1, At, B1); PG8_BAR; PG8_SCHED;
	s_setprio 1
	v_mfma_f32_16x16x32_bf16 v[128:131], v[158:161], v[190:193], v[128:131]
	v_mfma_f32_16x16x32_bf16 v[124:127], v[166:169], v[190:193], v[124:127]
	v_mfma_f32_16x16x32_bf16 v[112:115], v[158:161], v[198:201], v[112:115]
	v_mfma_f32_16x16x32_bf16 v[108:111], v[166:169], v[198:201], v[108:111]
	v_mfma_f32_16x16x32_bf16 v[96:99], v[158:161], v[206:209], v[96:99]
	v_mfma_f32_16x16x32_bf16 v[92:95], v[166:169], v[206:209], v[92:95]
	v_mfma_f32_16x16x32_bf16 v[80:83], v[158:161], v[214:217], v[80:83]
	v_mfma_f32_16x16x32_bf16 v[76:79], v[166:169], v[214:217], v[76:79]
	v_mfma_f32_16x16x32_bf16 v[128:131], v[162:165], v[194:197], v[128:131]
	v_mfma_f32_16x16x32_bf16 v[124:127], v[170:173], v[194:197], v[124:127]
	v_mfma_f32_16x16x32_bf16 v[112:115], v[162:165], v[202:205], v[112:115]
	v_mfma_f32_16x16x32_bf16 v[108:111], v[170:173], v[202:205], v[108:111]
	v_mfma_f32_16x16x32_bf16 v[96:99], v[162:165], v[210:213], v[96:99]
	v_mfma_f32_16x16x32_bf16 v[92:95], v[170:173], v[210:213], v[92:95]
	v_mfma_f32_16x16x32_bf16 v[80:83], v[162:165], v[218:221], v[80:83]
	v_mfma_f32_16x16x32_bf16 v[76:79], v[170:173], v[218:221], v[76:79]
	s_setprio 0
	s_setprio 1
	v_mfma_f32_16x16x32_bf16 v[120:123], v[174:177], v[190:193], v[120:123]
	v_mfma_f32_16x16x32_bf16 v[116:119], v[182:185], v[190:193], v[116:119]
	v_mfma_f32_16x16x32_bf16 v[104:107], v[174:177], v[198:201], v[104:107]
	v_mfma_f32_16x16x32_bf16 v[100:103], v[182:185], v[198:201], v[100:103]
	v_mfma_f32_16x16x32_bf16 v[88:91], v[174:177], v[206:209], v[88:91]
	v_mfma_f32_16x16x32_bf16 v[84:87], v[182:185], v[206:209], v[84:87]
	v_mfma_f32_16x16x32_bf16 v[72:75], v[174:177], v[214:217], v[72:75]
	v_mfma_f32_16x16x32_bf16 v[68:71], v[182:185], v[214:217], v[68:71]
	v_mfma_f32_16x16x32_bf16 v[120:123], v[178:181], v[194:197], v[120:123]
	v_mfma_f32_16x16x32_bf16 v[116:119], v[186:189], v[194:197], v[116:119]
	v_mfma_f32_16x16x32_bf16 v[104:107], v[178:181], v[202:205], v[104:107]
	v_mfma_f32_16x16x32_bf16 v[100:103], v[186:189], v[202:205], v[100:103]
	v_mfma_f32_16x16x32_bf16 v[88:91], v[178:181], v[210:213], v[88:91]
	v_mfma_f32_16x16x32_bf16 v[84:87], v[186:189], v[210:213], v[84:87]
	v_mfma_f32_16x16x32_bf16 v[72:75], v[178:181], v[218:221], v[72:75]
	v_mfma_f32_16x16x32_bf16 v[68:71], v[186:189], v[218:221], v[68:71]
	s_setprio 0
	s_barrier
	s_add_i32 s42, s69, s4
	s_add_u32 s98, vcc_lo, 0x80
	s_addc_u32 s99, vcc_hi, 0
	s_mov_b32 m0, s42
	ds_read_b128 v[190:193], v156 offset:49152
	ds_read_b128 v[194:197], v156 offset:50176
	ds_read_b128 v[198:201], v156 offset:51200
	ds_read_b128 v[202:205], v156 offset:52224
	ds_read_b128 v[206:209], v156 offset:53248
	ds_read_b128 v[210:213], v156 offset:54272
	ds_read_b128 v[214:217], v156 offset:55296
	ds_read_b128 v[218:221], v156 offset:56320
	global_load_lds_dwordx4 v134, s[98:99]
	s_add_i32 m0, s42, 0x2000
	s_add_u32 s42, vcc_lo, 0x80080
	s_addc_u32 s43, vcc_hi, 0
	s_add_i32 s69, s70, s4
	global_load_lds_dwordx4 v138, s[98:99]
	s_mov_b32 m0, s69
	s_nop 0
	global_load_lds_dwordx4 v134, s[42:43]
	s_add_i32 m0, s69, 0x2000
	s_nop 0
	global_load_lds_dwordx4 v138, s[42:43]
	s_waitcnt vmcnt(6) lgkmcnt(0)
	s_barrier
	s_setprio 1
	v_mfma_f32_16x16x32_bf16 v[64:67], v[158:161], v[190:193], v[64:67]
	v_mfma_f32_16x16x32_bf16 v[60:63], v[166:169], v[190:193], v[60:63]
	v_mfma_f32_16x16x32_bf16 v[48:51], v[158:161], v[198:201], v[48:51]
	v_mfma_f32_16x16x32_bf16 v[44:47], v[166:169], v[198:201], v[44:47]
	v_mfma_f32_16x16x32_bf16 v[32:35], v[158:161], v[206:209], v[32:35]
	v_mfma_f32_16x16x32_bf16 v[28:31], v[166:169], v[206:209], v[28:31]
	v_mfma_f32_16x16x32_bf16 v[16:19], v[158:161], v[214:217], v[16:19]
	v_mfma_f32_16x16x32_bf16 v[12:15], v[166:169], v[214:217], v[12:15]
	v_mfma_f32_16x16x32_bf16 v[64:67], v[162:165], v[194:197], v[64:67]
	v_mfma_f32_16x16x32_bf16 v[60:63], v[170:173], v[194:197], v[60:63]
	v_mfma_f32_16x16x32_bf16 v[48:51], v[162:165], v[202:205], v[48:51]
	v_mfma_f32_16x16x32_bf16 v[44:47], v[170:173], v[202:205], v[44:47]
	v_mfma_f32_16x16x32_bf16 v[32:35], v[162:165], v[210:213], v[32:35]
	v_mfma_f32_16x16x32_bf16 v[28:31], v[170:173], v[210:213], v[28:31]
	v_mfma_f32_16x16x32_bf16 v[16:19], v[162:165], v[218:221], v[16:19]
	v_mfma_f32_16x16x32_bf16 v[12:15], v[170:173], v[218:221], v[12:15]
	s_setprio 0
	s_setprio 1
	v_mfma_f32_16x16x32_bf16 v[56:59], v[174:177], v[190:193], v[56:59]
	v_mfma_f32_16x16x32_bf16 v[52:55], v[182:185], v[190:193], v[52:55]
	v_mfma_f32_16x16x32_bf16 v[40:43], v[174:177], v[198:201], v[40:43]
	v_mfma_f32_16x16x32_bf16 v[36:39], v[182:185], v[198:201], v[36:39]
	v_mfma_f32_16x16x32_bf16 v[24:27], v[174:177], v[206:209], v[24:27]
	v_mfma_f32_16x16x32_bf16 v[20:23], v[182:185], v[206:209], v[20:23]
	v_mfma_f32_16x16x32_bf16 v[6:9], v[174:177], v[214:217], v[8:11]
	v_mfma_f32_16x16x32_bf16 v[2:5], v[182:185], v[214:217], v[2:5]
	v_mfma_f32_16x16x32_bf16 v[56:59], v[178:181], v[194:197], v[56:59]
	v_mfma_f32_16x16x32_bf16 v[52:55], v[186:189], v[194:197], v[52:55]
	v_mfma_f32_16x16x32_bf16 v[40:43], v[178:181], v[202:205], v[40:43]
	v_mfma_f32_16x16x32_bf16 v[36:39], v[186:189], v[202:205], v[36:39]
	v_mfma_f32_16x16x32_bf16 v[24:27], v[178:181], v[210:213], v[24:27]
	v_mfma_f32_16x16x32_bf16 v[20:23], v[186:189], v[210:213], v[20:23]
	v_mfma_f32_16x16x32_bf16 v[8:11], v[178:181], v[218:221], v[6:9]
	v_mfma_f32_16x16x32_bf16 v[4:7], v[186:189], v[218:221], v[2:5]
	s_setprio 0
	s_barrier
	s_add_i32 s68, s68, 2
	s_add_u32 s18, s18, 0x100
	s_addc_u32 s19, s19, 0
	s_cmp_gt_u32 s68, 29
	s_cbranch_scc1 .LBB0_1220

; #define PG8_STAGE(bufoff, gbase, voff) do { _Pragma("unroll") for (int _i = 0; _i < 2; ++_i) \
;         __builtin_amdgcn_global_load_lds((const unsigned*)((const char*)(gbase) + (voff)[_i]), (PG8_LAS unsigned*)(lds + (bufoff) + ldsw + _i * 8192), 16, 0, 0); } while (0)
; #define PG8_LDA(dst, b, h) do { _Pragma("unroll") for (int m = 0; m < 4; ++m) _Pragma("unroll") for (int k = 0; k < 2; ++k) dst[m][k] = *(const PG8_LAS bf16x8*)(lds + PG8_SA(b, h) + aoff + m * 2048 + k * 1024); } while (0)
; #define PG8_LDB(dst, b, h) do { _Pragma("unroll") for (int n = 0; n < 2; ++n) _Pragma("unroll") for (int k = 0; k < 2; ++k) dst[n][k] = *(const PG8_LAS bf16x8*)(lds + PG8_SB(b, h) + boff + n * 2048 + k * 1024); } while (0)
; #define PG8_MMA(ai, bj, At, Bt) do { __builtin_amdgcn_s_setprio(1); _Pragma("unroll") for (int m = 0; m < 4; ++m) _Pragma("unroll") for (int n = 0; n < 2; ++n) _Pragma("unroll") for (int k = 0; k < 2; ++k) \
;         acc[ai][bj][m][n] = __builtin_amdgcn_mfma_f32_16x16x32_bf16(Bt[n][k], At[m][k], acc[ai][bj][m][n], 0, 0, 0); __builtin_amdgcn_s_setprio(0); } while (0)
; #define PG8_WAIT_V(n) asm volatile("s_waitcnt vmcnt(" #n ")" ::: "memory")
; #define PG8_WAIT_L(n) asm volatile("s_waitcnt lgkmcnt(" #n ")" ::: "memory")
; #define PG8_BAR __builtin_amdgcn_s_barrier()
; #define PG8_SCHED __builtin_amdgcn_sched_barrier(0)
; template <class Epi, class Sched, bool ALIGN_EPI = false, bool SP2 = false>
; __device__ __forceinline__ void gemm_phase(PG8_LAS unsigned char* lds, const Gemm g, const Sched& S, const Epi& E) {
;     ...
;             PG8_LDB(B0, 0, 0); PG8_LDB(B1, 0, 1); PG8_SCHED; PG8_LDA(At, 0, 0); PG8_STAGE(PG8_SA(1, 1), a1 + hstepA, voffA);
;             PG8_WAIT_V(8); PG8_WAIT_L(0); PG8_BAR; PG8_MMA(0, 0, At, B0); PG8_MMA(0, 1, At, B1); PG8_BAR; PG8_SCHED;
;             PG8_LDA(At, 0, 1); PG8_STAGE(PG8_SB(0, 0), b2, voffB); PG8_STAGE(PG8_SB(0, 1), b2 + hstepB, voffB); PG8_STAGE(PG8_SA(0, 0), a2, voffA);
;             PG8_WAIT_V(8); PG8_WAIT_L(0); PG8_BAR; PG8_MMA(1, 0, At, B0); PG8_MMA(1, 1, At, B1); PG8_BAR; PG8_SCHED;
;             PG8_LDB(B0, 1, 0); PG8_LDB(B1, 1, 1); PG8_SCHED; PG8_LDA(At, 1, 0); PG8_STAGE(PG8_SA(0, 1), a2 + hstepA, voffA);
;             PG8_WAIT_V(8); PG8_WAIT_L(0); PG8_BAR; PG8_MMA(0, 0, At, B0); PG8_MMA(0, 1, At, B1); PG8_BAR; PG8_SCHED;
.LBB0_1309:
	ds_read_b128 v[128:131], v161
	ds_read_b128 v[132:135], v161 offset:1024
	ds_read_b128 v[148:151], v161 offset:2048
	ds_read_b128 v[152:155], v161 offset:3072
	ds_read_b128 v[166:169], v162
	ds_read_b128 v[170:173], v162 offset:1024
	ds_read_b128 v[174:177], v162 offset:2048
	ds_read_b128 v[178:181], v162 offset:3072
	s_add_u32 s16, s12, 0xfff80080
	s_addc_u32 s17, s13, -1
	s_cmp_eq_u32 s65, 28
	s_cselect_b32 s19, s39, s17
	s_cselect_b32 s18, s59, s16
	s_cselect_b32 s17, s37, s63
	s_cselect_b32 s16, s61, s62
	ds_read_b128 v[182:185], v163
	ds_read_b128 v[186:189], v163 offset:1024
	ds_read_b128 v[190:193], v163 offset:2048
	ds_read_b128 v[194:197], v163 offset:3072
	ds_read_b128 v[198:201], v163 offset:4096
	ds_read_b128 v[202:205], v163 offset:5120
	ds_read_b128 v[206:209], v163 offset:6144
	ds_read_b128 v[210:213], v163 offset:7168
	s_add_u32 s98, s12, 0xfff80000
	s_addc_u32 s99, s13, -1
	s_mov_b32 m0, s33
	s_nop 0
	global_load_lds_dwordx4 v136, s[98:99]
	s_mov_b32 m0, s34
	s_nop 0
	global_load_lds_dwordx4 v140, s[98:99]
	s_add_i32 m0, s5, 0xc000
	s_nop 0
	global_load_lds_dwordx4 v144, s[12:13]
	s_add_i32 m0, s5, 0xe000
	s_nop 0
	global_load_lds_dwordx4 v146, s[12:13]
	s_waitcnt vmcnt(8) lgkmcnt(0)
	s_barrier
	s_setprio 1
	v_mfma_f32_16x16x32_bf16 v[124:127], v[128:131], v[182:185], v[124:127]
	v_mfma_f32_16x16x32_bf16 v[120:123], v[148:151], v[182:185], v[120:123]
	v_mfma_f32_16x16x32_bf16 v[108:111], v[128:131], v[190:193], v[108:111]
	v_mfma_f32_16x16x32_bf16 v[104:107], v[148:151], v[190:193], v[104:107]
	v_mfma_f32_16x16x32_bf16 v[92:95], v[128:131], v[198:201], v[92:95]
	v_mfma_f32_16x16x32_bf16 v[88:91], v[148:151], v[198:201], v[88:91]
	v_mfma_f32_16x16x32_bf16 v[76:79], v[128:131], v[206:209], v[76:79]
	v_mfma_f32_16x16x32_bf16 v[72:75], v[148:151], v[206:209], v[72:75]
	v_mfma_f32_16x16x32_bf16 v[124:127], v[132:135], v[186:189], v[124:127]
	v_mfma_f32_16x16x32_bf16 v[120:123], v[152:155], v[186:189], v[120:123]
	v_mfma_f32_16x16x32_bf16 v[108:111], v[132:135], v[194:197], v[108:111]
	v_mfma_f32_16x16x32_bf16 v[104:107], v[152:155], v[194:197], v[104:107]
	v_mfma_f32_16x16x32_bf16 v[92:95], v[132:135], v[202:205], v[92:95]
	v_mfma_f32_16x16x32_bf16 v[88:91], v[152:155], v[202:205], v[88:91]
	v_mfma_f32_16x16x32_bf16 v[76:79], v[132:135], v[210:213], v[76:79]
	v_mfma_f32_16x16x32_bf16 v[72:75], v[152:155], v[210:213], v[72:75]
	s_setprio 0
	s_setprio 1
	v_mfma_f32_16x16x32_bf16 v[116:119], v[166:169], v[182:185], v[116:119]
	v_mfma_f32_16x16x32_bf16 v[112:115], v[174:177], v[182:185], v[112:115]
	v_mfma_f32_16x16x32_bf16 v[100:103], v[166:169], v[190:193], v[100:103]
	v_mfma_f32_16x16x32_bf16 v[96:99], v[174:177], v[190:193], v[96:99]
	v_mfma_f32_16x16x32_bf16 v[84:87], v[166:169], v[198:201], v[84:87]
	v_mfma_f32_16x16x32_bf16 v[80:83], v[174:177], v[198:201], v[80:83]
	v_mfma_f32_16x16x32_bf16 v[68:71], v[166:169], v[206:209], v[68:71]
	v_mfma_f32_16x16x32_bf16 v[64:67], v[174:177], v[206:209], v[64:67]
	v_mfma_f32_16x16x32_bf16 v[116:119], v[170:173], v[186:189], v[116:119]
	v_mfma_f32_16x16x32_bf16 v[112:115], v[178:181], v[186:189], v[112:115]
	v_mfma_f32_16x16x32_bf16 v[100:103], v[170:173], v[194:197], v[100:103]
	v_mfma_f32_16x16x32_bf16 v[96:99], v[178:181], v[194:197], v[96:99]
	v_mfma_f32_16x16x32_bf16 v[84:87], v[170:173], v[202:205], v[84:87]
	v_mfma_f32_16x16x32_bf16 v[80:83], v[178:181], v[202:205], v[80:83]
	v_mfma_f32_16x16x32_bf16 v[68:71], v[170:173], v[210:213], v[68:71]
	v_mfma_f32_16x16x32_bf16 v[64:67], v[178:181], v[210:213], v[64:67]
	s_setprio 0
	s_barrier
	s_add_i32 s66, s56, s4
	s_mov_b32 m0, s66
	ds_read_b128 v[182:185], v163 offset:16384
	ds_read_b128 v[186:189], v163 offset:17408
	ds_read_b128 v[190:193], v163 offset:18432
	ds_read_b128 v[194:197], v163 offset:19456
	ds_read_b128 v[198:201], v163 offset:20480
	ds_read_b128 v[202:205], v163 offset:21504
	ds_read_b128 v[206:209], v163 offset:22528
	ds_read_b128 v[210:213], v163 offset:23552
	global_load_lds_dwordx4 v138, s[16:17]
	s_add_i32 m0, s66, 0x2000
	s_add_u32 s66, s16, 0x80000
	s_addc_u32 s67, s17, 0
	s_add_i32 s68, s57, s4
	global_load_lds_dwordx4 v142, s[16:17]
	s_mov_b32 m0, s68
	s_nop 0
	global_load_lds_dwordx4 v138, s[66:67]
	s_add_i32 m0, s68, 0x2000
	s_nop 0
	global_load_lds_dwordx4 v142, s[66:67]
	s_waitcnt vmcnt(6) lgkmcnt(0)
	s_barrier
	s_setprio 1
	v_mfma_f32_16x16x32_bf16 v[60:63], v[128:131], v[182:185], v[60:63]
	v_mfma_f32_16x16x32_bf16 v[56:59], v[148:151], v[182:185], v[56:59]
	v_mfma_f32_16x16x32_bf16 v[44:47], v[128:131], v[190:193], v[44:47]
	v_mfma_f32_16x16x32_bf16 v[40:43], v[148:151], v[190:193], v[40:43]
	v_mfma_f32_16x16x32_bf16 v[28:31], v[128:131], v[198:201], v[28:31]
	v_mfma_f32_16x16x32_bf16 v[24:27], v[148:151], v[198:201], v[24:27]
	v_mfma_f32_16x16x32_bf16 v[12:15], v[128:131], v[206:209], v[12:15]
	v_mfma_f32_16x16x32_bf16 v[8:11], v[148:151], v[206:209], v[8:11]
	v_mfma_f32_16x16x32_bf16 v[60:63], v[132:135], v[186:189], v[60:63]
	v_mfma_f32_16x16x32_bf16 v[56:59], v[152:155], v[186:189], v[56:59]
	v_mfma_f32_16x16x32_bf16 v[44:47], v[132:135], v[194:197], v[44:47]
	v_mfma_f32_16x16x32_bf16 v[40:43], v[152:155], v[194:197], v[40:43]
	v_mfma_f32_16x16x32_bf16 v[28:31], v[132:135], v[202:205], v[28:31]
	v_mfma_f32_16x16x32_bf16 v[24:27], v[152:155], v[202:205], v[24:27]
	v_mfma_f32_16x16x32_bf16 v[12:15], v[132:135], v[210:213], v[12:15]
	v_mfma_f32_16x16x32_bf16 v[8:11], v[152:155], v[210:213], v[8:11]
	s_setprio 0
	s_setprio 1
	v_mfma_f32_16x16x32_bf16 v[52:55], v[166:169], v[182:185], v[52:55]
	v_mfma_f32_16x16x32_bf16 v[48:51], v[174:177], v[182:185], v[48:51]
	v_mfma_f32_16x16x32_bf16 v[36:39], v[166:169], v[190:193], v[36:39]
	v_mfma_f32_16x16x32_bf16 v[32:35], v[174:177], v[190:193], v[32:35]
	v_mfma_f32_16x16x32_bf16 v[20:23], v[166:169], v[198:201], v[20:23]
	v_mfma_f32_16x16x32_bf16 v[16:19], v[174:177], v[198:201], v[16:19]
	v_mfma_f32_16x16x32_bf16 v[4:7], v[166:169], v[206:209], v[4:7]
	v_mfma_f32_16x16x32_bf16 v[0:3], v[174:177], v[206:209], v[0:3]
	v_mfma_f32_16x16x32_bf16 v[52:55], v[170:173], v[186:189], v[52:55]
	v_mfma_f32_16x16x32_bf16 v[48:51], v[178:181], v[186:189], v[48:51]
	v_mfma_f32_16x16x32_bf16 v[36:39], v[170:173], v[194:197], v[36:39]
	v_mfma_f32_16x16x32_bf16 v[32:35], v[178:181], v[194:197], v[32:35]
	v_mfma_f32_16x16x32_bf16 v[20:23], v[170:173], v[202:205], v[20:23]
	v_mfma_f32_16x16x32_bf16 v[16:19], v[178:181], v[202:205], v[16:19]
	v_mfma_f32_16x16x32_bf16 v[4:7], v[170:173], v[210:213], v[4:7]
	v_mfma_f32_16x16x32_bf16 v[0:3], v[178:181], v[210:213], v[0:3]
	s_setprio 0
	s_barrier
; #define PG8_STAGE(bufoff, gbase, voff) do { _Pragma("unroll") for (int _i = 0; _i < 2; ++_i) \
;         __builtin_amdgcn_global_load_lds((const unsigned*)((const char*)(gbase) + (voff)[_i]), (PG8_LAS unsigned*)(lds + (bufoff) + ldsw + _i * 8192), 16, 0, 0); } while (0)
; #define PG8_LDA(dst, b, h) do { _Pragma("unroll") for (int m = 0; m < 4; ++m) _Pragma("unroll") for (int k = 0; k < 2; ++k) dst[m][k] = *(const PG8_LAS bf16x8*)(lds + PG8_SA(b, h) + aoff + m * 2048 + k * 1024); } while (0)
; #define PG8_WAIT_V(n) asm volatile("s_waitcnt vmcnt(" #n ")" ::: "memory")
; #define PG8_BAR __builtin_amdgcn_s_barrier()
; template <class Epi, class Sched, bool ALIGN_EPI = false, bool SP2 = false>
; __device__ __forceinline__ void gemm_phase(PG8_LAS unsigned char* lds, const Gemm g, const Sched& S, const Epi& E) {
;     ...
;         for (int t = 0; t < nt; t += 2) {
;             const bool last = (t == nt - 2);
;             if constexpr (Epi::HAS_MID) { if (t == E.mid_t) E.mid(acc, cur, wr, wc, fr, fq); }
;             const char* a1 = cA + (size_t)(t + 1) * kstep;
;             const char* a2 = last ? nA : cA + (size_t)(t + 2) * kstep; const char* b2 = last ? nB : cB + (size_t)(t + 2) * kstep;
;             const char* a3 = a2 + kstep; const char* b3 = b2 + kstep;
;             if (last && has_next) S.a_ready(nxt);
;             if constexpr (SP2) {
;             PG8_LDB(B0, 0, 0); PG8_LDB(B1, 0, 1); PG8_SCHED; PG8_LDA(At, 0, 0); PG8_STAGE(PG8_SA(1, 1), a1 + hstepA, voffA);
;             PG8_WAIT_V(8); PG8_WAIT_L(0); PG8_BAR; PG8_MMA(0, 0, At, B0); PG8_MMA(0, 1, At, B1); PG8_BAR; PG8_SCHED;
;             PG8_LDA(At, 0, 1); PG8_STAGE(PG8_SB(0, 0), b2, voffB); PG8_STAGE(PG8_SB(0, 1), b2 + hstepB, voffB); PG8_STAGE(PG8_SA(0, 0), a2, voffA);
;             PG8_WAIT_V(8); PG8_WAIT_L(0); PG8_BAR; PG8_MMA(1, 0, At, B0); PG8_MMA(1, 1, At, B1); PG8_BAR; PG8_SCHED;
;             PG8_LDB(B0, 1, 0); PG8_LDB(B1, 1, 1); PG8_SCHED; PG8_LDA(At, 1, 0); PG8_STAGE(PG8_SA(0, 1), a2 + hstepA, voffA);
;             PG8_WAIT_V(8); PG8_WAIT_L(0); PG8_BAR; PG8_MMA(0, 0, At, B0); PG8_MMA(0, 1, At, B1); PG8_BAR; PG8_SCHED;
;             PG8_LDA(At, 1, 1); PG8_STAGE(PG8_SB(1, 0), b3, voffB); PG8_STAGE(PG8_SB(1, 1), b3 + hstepB, voffB); PG8_STAGE(PG8_SA(1, 0), a3, voffA);
;             PG8_WAIT_V(8); PG8_WAIT_L(0); PG8_BAR; PG8_MMA(1, 0, At, B0); PG8_MMA(1, 1, At, B1); PG8_BAR; PG8_SCHED;
	s_add_i32 s66, 0, 0x18000
	s_add_i32 s67, 0, 0x1c000
	v_add_u32_e32 v152, s66, v160
	v_add_u32_e32 v165, s67, v160
	ds_read_b128 v[128:131], v152
	ds_read_b128 v[132:135], v152 offset:1024
	ds_read_b128 v[148:151], v152 offset:2048
	ds_read_b128 v[152:155], v152 offset:3072
	ds_read_b128 v[166:169], v165
	ds_read_b128 v[170:173], v165 offset:1024
	ds_read_b128 v[174:177], v165 offset:2048
	ds_read_b128 v[178:181], v165 offset:3072
	s_mov_b64 s[100:101], s[18:19]
	s_add_u32 s18, s18, 0x80000
	s_addc_u32 s19, s19, 0
	ds_read_b128 v[182:185], v163 offset:32768
	ds_read_b128 v[186:189], v163 offset:33792
	ds_read_b128 v[190:193], v163 offset:34816
	ds_read_b128 v[194:197], v163 offset:35840
	ds_read_b128 v[198:201], v163 offset:36864
	ds_read_b128 v[202:205], v163 offset:37888
	ds_read_b128 v[206:209], v163 offset:38912
	ds_read_b128 v[210:213], v163 offset:39936
	s_mov_b32 m0, s5
	s_nop 0
	global_load_lds_dwordx4 v136, s[100:101]
	s_mov_b32 m0, s6
	s_nop 0
	global_load_lds_dwordx4 v140, s[100:101]
	s_mov_b32 m0, s7
	s_nop 0
	global_load_lds_dwordx4 v136, s[18:19]
	s_mov_b32 m0, s20
	s_nop 0
	global_load_lds_dwordx4 v140, s[18:19]
	s_waitcnt vmcnt(8) lgkmcnt(0)
	s_barrier
	s_setprio 1
	v_mfma_f32_16x16x32_bf16 v[124:127], v[128:131], v[182:185], v[124:127]
	v_mfma_f32_16x16x32_bf16 v[120:123], v[148:151], v[182:185], v[120:123]
	v_mfma_f32_16x16x32_bf16 v[108:111], v[128:131], v[190:193], v[108:111]
	v_mfma_f32_16x16x32_bf16 v[104:107], v[148:151], v[190:193], v[104:107]
	v_mfma_f32_16x16x32_bf16 v[92:95], v[128:131], v[198:201], v[92:95]
	v_mfma_f32_16x16x32_bf16 v[88:91], v[148:151], v[198:201], v[88:91]
	v_mfma_f32_16x16x32_bf16 v[76:79], v[128:131], v[206:209], v[76:79]
	v_mfma_f32_16x16x32_bf16 v[72:75], v[148:151], v[206:209], v[72:75]
	v_mfma_f32_16x16x32_bf16 v[124:127], v[132:135], v[186:189], v[124:127]
	v_mfma_f32_16x16x32_bf16 v[120:123], v[152:155], v[186:189], v[120:123]
	v_mfma_f32_16x16x32_bf16 v[108:111], v[132:135], v[194:197], v[108:111]
	v_mfma_f32_16x16x32_bf16 v[104:107], v[152:155], v[194:197], v[104:107]
	v_mfma_f32_16x16x32_bf16 v[92:95], v[132:135], v[202:205], v[92:95]
	v_mfma_f32_16x16x32_bf16 v[88:91], v[152:155], v[202:205], v[88:91]
	v_mfma_f32_16x16x32_bf16 v[76:79], v[132:135], v[210:213], v[76:79]
	v_mfma_f32_16x16x32_bf16 v[72:75], v[152:155], v[210:213], v[72:75]
	s_setprio 0
	s_setprio 1
	v_mfma_f32_16x16x32_bf16 v[116:119], v[166:169], v[182:185], v[116:119]
	v_mfma_f32_16x16x32_bf16 v[112:115], v[174:177], v[182:185], v[112:115]
	v_mfma_f32_16x16x32_bf16 v[100:103], v[166:169], v[190:193], v[100:103]
	v_mfma_f32_16x16x32_bf16 v[96:99], v[174:177], v[190:193], v[96:99]
	v_mfma_f32_16x16x32_bf16 v[84:87], v[166:169], v[198:201], v[84:87]
	v_mfma_f32_16x16x32_bf16 v[80:83], v[174:177], v[198:201], v[80:83]
	v_mfma_f32_16x16x32_bf16 v[68:71], v[166:169], v[206:209], v[68:71]
	v_mfma_f32_16x16x32_bf16 v[64:67], v[174:177], v[206:209], v[64:67]
	v_mfma_f32_16x16x32_bf16 v[116:119], v[170:173], v[186:189], v[116:119]
	v_mfma_f32_16x16x32_bf16 v[112:115], v[178:181], v[186:189], v[112:115]
	v_mfma_f32_16x16x32_bf16 v[100:103], v[170:173], v[194:197], v[100:103]
	v_mfma_f32_16x16x32_bf16 v[96:99], v[178:181], v[194:197], v[96:99]
	v_mfma_f32_16x16x32_bf16 v[84:87], v[170:173], v[202:205], v[84:87]
	v_mfma_f32_16x16x32_bf16 v[80:83], v[178:181], v[202:205], v[80:83]
	v_mfma_f32_16x16x32_bf16 v[68:71], v[170:173], v[210:213], v[68:71]
	v_mfma_f32_16x16x32_bf16 v[64:67], v[178:181], v[210:213], v[64:67]
	s_setprio 0
	s_barrier
	s_add_i32 s18, s66, s4
	s_add_u32 s98, s16, 0x80
	s_addc_u32 s99, s17, 0
	s_mov_b32 m0, s18
	ds_read_b128 v[182:185], v163 offset:49152
	ds_read_b128 v[186:189], v163 offset:50176
	ds_read_b128 v[190:193], v163 offset:51200
	ds_read_b128 v[194:197], v163 offset:52224
	ds_read_b128 v[198:201], v163 offset:53248
	ds_read_b128 v[202:205], v163 offset:54272
	ds_read_b128 v[206:209], v163 offset:55296
	ds_read_b128 v[210:213], v163 offset:56320
	global_load_lds_dwordx4 v138, s[98:99]
	s_add_i32 m0, s18, 0x2000
	s_add_u32 s16, s16, 0x80080
	s_addc_u32 s17, s17, 0
	s_add_i32 s18, s67, s4
	global_load_lds_dwordx4 v142, s[98:99]
	s_mov_b32 m0, s18
	s_nop 0
	global_load_lds_dwordx4 v138, s[16:17]
	s_add_i32 m0, s18, 0x2000
	s_nop 0
	global_load_lds_dwordx4 v142, s[16:17]
	s_waitcnt vmcnt(6) lgkmcnt(0)
	s_barrier
	s_setprio 1
	v_mfma_f32_16x16x32_bf16 v[60:63], v[128:131], v[182:185], v[60:63]
	v_mfma_f32_16x16x32_bf16 v[56:59], v[148:151], v[182:185], v[56:59]
	v_mfma_f32_16x16x32_bf16 v[44:47], v[128:131], v[190:193], v[44:47]
	v_mfma_f32_16x16x32_bf16 v[40:43], v[148:151], v[190:193], v[40:43]
	v_mfma_f32_16x16x32_bf16 v[28:31], v[128:131], v[198:201], v[28:31]
	v_mfma_f32_16x16x32_bf16 v[24:27], v[148:151], v[198:201], v[24:27]
	v_mfma_f32_16x16x32_bf16 v[12:15], v[128:131], v[206:209], v[12:15]
	v_mfma_f32_16x16x32_bf16 v[8:11], v[148:151], v[206:209], v[8:11]
	v_mfma_f32_16x16x32_bf16 v[60:63], v[132:135], v[186:189], v[60:63]
	v_mfma_f32_16x16x32_bf16 v[56:59], v[152:155], v[186:189], v[56:59]
	v_mfma_f32_16x16x32_bf16 v[44:47], v[132:135], v[194:197], v[44:47]
	v_mfma_f32_16x16x32_bf16 v[40:43], v[152:155], v[194:197], v[40:43]
	v_mfma_f32_16x16x32_bf16 v[28:31], v[132:135], v[202:205], v[28:31]
	v_mfma_f32_16x16x32_bf16 v[24:27], v[152:155], v[202:205], v[24:27]
	v_mfma_f32_16x16x32_bf16 v[12:15], v[132:135], v[210:213], v[12:15]
	v_mfma_f32_16x16x32_bf16 v[8:11], v[152:155], v[210:213], v[8:11]
	s_setprio 0
	s_setprio 1
	v_mfma_f32_16x16x32_bf16 v[52:55], v[166:169], v[182:185], v[52:55]
	v_mfma_f32_16x16x32_bf16 v[48:51], v[174:177], v[182:185], v[48:51]
	v_mfma_f32_16x16x32_bf16 v[36:39], v[166:169], v[190:193], v[36:39]
	v_mfma_f32_16x16x32_bf16 v[32:35], v[174:177], v[190:193], v[32:35]
	v_mfma_f32_16x16x32_bf16 v[20:23], v[166:169], v[198:201], v[20:23]
	v_mfma_f32_16x16x32_bf16 v[16:19], v[174:177], v[198:201], v[16:19]
	v_mfma_f32_16x16x32_bf16 v[4:7], v[166:169], v[206:209], v[4:7]
	v_mfma_f32_16x16x32_bf16 v[0:3], v[174:177], v[206:209], v[0:3]
	v_mfma_f32_16x16x32_bf16 v[52:55], v[170:173], v[186:189], v[52:55]
	v_mfma_f32_16x16x32_bf16 v[48:51], v[178:181], v[186:189], v[48:51]
	v_mfma_f32_16x16x32_bf16 v[36:39], v[170:173], v[194:197], v[36:39]
	v_mfma_f32_16x16x32_bf16 v[32:35], v[178:181], v[194:197], v[32:35]
	v_mfma_f32_16x16x32_bf16 v[20:23], v[170:173], v[202:205], v[20:23]
	v_mfma_f32_16x16x32_bf16 v[16:19], v[178:181], v[202:205], v[16:19]
	v_mfma_f32_16x16x32_bf16 v[4:7], v[170:173], v[210:213], v[4:7]
	v_mfma_f32_16x16x32_bf16 v[0:3], v[178:181], v[210:213], v[0:3]
	s_setprio 0
	s_barrier
	s_add_i32 s65, s65, 2
	s_add_u32 s12, s12, 0x100
	s_addc_u32 s13, s13, 0
	s_add_u32 s62, s62, 0x100
	s_addc_u32 s63, s63, 0
	s_cmp_gt_u32 s65, 29
	s_cbranch_scc0 .LBB0_1309
	s_and_b64 vcc, exec, s[26:27]
	s_cbranch_vccz .LBB0_1312
	s_barrier

; #define PG8_STAGE(bufoff, gbase, voff) do { _Pragma("unroll") for (int _i = 0; _i < 2; ++_i) \
;         __builtin_amdgcn_global_load_lds((const unsigned*)((const char*)(gbase) + (voff)[_i]), (PG8_LAS unsigned*)(lds + (bufoff) + ldsw + _i * 8192), 16, 0, 0); } while (0)
; #define PG8_LDA(dst, b, h) do { _Pragma("unroll") for (int m = 0; m < 4; ++m) _Pragma("unroll") for (int k = 0; k < 2; ++k) dst[m][k] = *(const PG8_LAS bf16x8*)(lds + PG8_SA(b, h) + aoff + m * 2048 + k * 1024); } while (0)
; #define PG8_LDB(dst, b, h) do { _Pragma("unroll") for (int n = 0; n < 2; ++n) _Pragma("unroll") for (int k = 0; k < 2; ++k) dst[n][k] = *(const PG8_LAS bf16x8*)(lds + PG8_SB(b, h) + boff + n * 2048 + k * 1024); } while (0)
; #define PG8_WAIT_V(n) asm volatile("s_waitcnt vmcnt(" #n ")" ::: "memory")
; #define PG8_WAIT_L(n) asm volatile("s_waitcnt lgkmcnt(" #n ")" ::: "memory")
; #define PG8_BAR __builtin_amdgcn_s_barrier()
; #define PG8_SCHED __builtin_amdgcn_sched_barrier(0)
; template <class Epi, class Sched, bool ALIGN_EPI = false, bool SP2 = false>
; __device__ __forceinline__ void gemm_phase(PG8_LAS unsigned char* lds, const Gemm g, const Sched& S, const Epi& E) {
;     ...
;         const char* nA = has_next ? (const char*)g.A + (size_t)nxt.pm * tstepA : cA; const char* nB = has_next ? (const char*)g.Bt + (size_t)nxt.pn * tstepB : cB;
;         for (int t = 0; t < nt; t += 2) {
;             const bool last = (t == nt - 2);
;             if constexpr (Epi::HAS_MID) { if (t == E.mid_t) E.mid(acc, cur, wr, wc, fr, fq); }
;             const char* a1 = cA + (size_t)(t + 1) * kstep;
;             const char* a2 = last ? nA : cA + (size_t)(t + 2) * kstep; const char* b2 = last ? nB : cB + (size_t)(t + 2) * kstep;
;             const char* a3 = a2 + kstep; const char* b3 = b2 + kstep;
;             if (last && has_next) S.a_ready(nxt);
;             if constexpr (SP2) {
;             PG8_LDB(B0, 0, 0); PG8_LDB(B1, 0, 1); PG8_SCHED; PG8_LDA(At, 0, 0); PG8_STAGE(PG8_SA(1, 1), a1 + hstepA, voffA);
;             PG8_WAIT_V(8); PG8_WAIT_L(0); PG8_BAR; PG8_MMA(0, 0, At, B0); PG8_MMA(0, 1, At, B1); PG8_BAR; PG8_SCHED;
;             PG8_LDA(At, 0, 1); PG8_STAGE(PG8_SB(0, 0), b2, voffB); PG8_STAGE(PG8_SB(0, 1), b2 + hstepB, voffB); PG8_STAGE(PG8_SA(0, 0), a2, voffA);
;             PG8_WAIT_V(8); PG8_WAIT_L(0); PG8_BAR; PG8_MMA(1, 0, At, B0); PG8_MMA(1, 1, At, B1); PG8_BAR; PG8_SCHED;
.LBB0_1738:
	ds_read_b128 v[144:147], v151
	ds_read_b128 v[154:157], v151 offset:1024
	ds_read_b128 v[158:161], v151 offset:2048
	ds_read_b128 v[162:165], v151 offset:3072
	ds_read_b128 v[166:169], v152
	ds_read_b128 v[170:173], v152 offset:1024
	ds_read_b128 v[174:177], v152 offset:2048
	ds_read_b128 v[178:181], v152 offset:3072
	s_add_u32 s34, s20, 0xfffe0080
	s_addc_u32 s35, s21, -1
	s_cmp_eq_u32 s57, 4
	s_cselect_b32 s39, s13, s35
	s_cselect_b32 s38, s27, s34
	s_cselect_b32 s35, s25, s56
	s_cselect_b32 s34, s52, s53
	ds_read_b128 v[182:185], v153
	ds_read_b128 v[186:189], v153 offset:1024
	ds_read_b128 v[190:193], v153 offset:2048
	ds_read_b128 v[194:197], v153 offset:3072
	ds_read_b128 v[198:201], v153 offset:4096
	ds_read_b128 v[202:205], v153 offset:5120
	ds_read_b128 v[206:209], v153 offset:6144
	ds_read_b128 v[210:213], v153 offset:7168
	s_add_u32 s98, s20, 0xfffe0000
	s_addc_u32 s99, s21, -1
	s_mov_b32 m0, s42
	s_nop 0
	global_load_lds_dwordx4 v128, s[98:99]
	s_mov_b32 m0, s43
	s_nop 0
	global_load_lds_dwordx4 v132, s[98:99]
	s_add_i32 m0, s5, 0xc000
	s_nop 0
	global_load_lds_dwordx4 v136, s[20:21]
	s_add_i32 m0, s5, 0xe000
	s_nop 0
	global_load_lds_dwordx4 v138, s[20:21]
	s_waitcnt vmcnt(8) lgkmcnt(0)
	s_barrier
	s_setprio 1
	v_mfma_f32_16x16x32_bf16 v[124:127], v[144:147], v[182:185], v[124:127]
	v_mfma_f32_16x16x32_bf16 v[120:123], v[158:161], v[182:185], v[120:123]
	v_mfma_f32_16x16x32_bf16 v[108:111], v[144:147], v[190:193], v[108:111]
	v_mfma_f32_16x16x32_bf16 v[104:107], v[158:161], v[190:193], v[104:107]
	v_mfma_f32_16x16x32_bf16 v[92:95], v[144:147], v[198:201], v[92:95]
	v_mfma_f32_16x16x32_bf16 v[88:91], v[158:161], v[198:201], v[88:91]
	v_mfma_f32_16x16x32_bf16 v[76:79], v[144:147], v[206:209], v[76:79]
	v_mfma_f32_16x16x32_bf16 v[72:75], v[158:161], v[206:209], v[72:75]
	v_mfma_f32_16x16x32_bf16 v[124:127], v[154:157], v[186:189], v[124:127]
	v_mfma_f32_16x16x32_bf16 v[120:123], v[162:165], v[186:189], v[120:123]
	v_mfma_f32_16x16x32_bf16 v[108:111], v[154:157], v[194:197], v[108:111]
	v_mfma_f32_16x16x32_bf16 v[104:107], v[162:165], v[194:197], v[104:107]
	v_mfma_f32_16x16x32_bf16 v[92:95], v[154:157], v[202:205], v[92:95]
	v_mfma_f32_16x16x32_bf16 v[88:91], v[162:165], v[202:205], v[88:91]
	v_mfma_f32_16x16x32_bf16 v[76:79], v[154:157], v[210:213], v[76:79]
	v_mfma_f32_16x16x32_bf16 v[72:75], v[162:165], v[210:213], v[72:75]
	s_setprio 0
	s_setprio 1
	v_mfma_f32_16x16x32_bf16 v[116:119], v[166:169], v[182:185], v[116:119]
	v_mfma_f32_16x16x32_bf16 v[112:115], v[174:177], v[182:185], v[112:115]
	v_mfma_f32_16x16x32_bf16 v[100:103], v[166:169], v[190:193], v[100:103]
	v_mfma_f32_16x16x32_bf16 v[96:99], v[174:177], v[190:193], v[96:99]
	v_mfma_f32_16x16x32_bf16 v[84:87], v[166:169], v[198:201], v[84:87]
	v_mfma_f32_16x16x32_bf16 v[80:83], v[174:177], v[198:201], v[80:83]
	v_mfma_f32_16x16x32_bf16 v[68:71], v[166:169], v[206:209], v[68:71]
	v_mfma_f32_16x16x32_bf16 v[64:67], v[174:177], v[206:209], v[64:67]
	v_mfma_f32_16x16x32_bf16 v[116:119], v[170:173], v[186:189], v[116:119]
	v_mfma_f32_16x16x32_bf16 v[112:115], v[178:181], v[186:189], v[112:115]
	v_mfma_f32_16x16x32_bf16 v[100:103], v[170:173], v[194:197], v[100:103]
	v_mfma_f32_16x16x32_bf16 v[96:99], v[178:181], v[194:197], v[96:99]
	v_mfma_f32_16x16x32_bf16 v[84:87], v[170:173], v[202:205], v[84:87]
	v_mfma_f32_16x16x32_bf16 v[80:83], v[178:181], v[202:205], v[80:83]
	v_mfma_f32_16x16x32_bf16 v[68:71], v[170:173], v[210:213], v[68:71]
	v_mfma_f32_16x16x32_bf16 v[64:67], v[178:181], v[210:213], v[64:67]
	s_setprio 0
	s_barrier
	s_add_i32 s58, s47, s4
	s_mov_b32 m0, s58
	ds_read_b128 v[182:185], v153 offset:16384
	ds_read_b128 v[186:189], v153 offset:17408
	ds_read_b128 v[190:193], v153 offset:18432
	ds_read_b128 v[194:197], v153 offset:19456
	ds_read_b128 v[198:201], v153 offset:20480
	ds_read_b128 v[202:205], v153 offset:21504
	ds_read_b128 v[206:209], v153 offset:22528
	ds_read_b128 v[210:213], v153 offset:23552
	global_load_lds_dwordx4 v130, s[34:35]
	s_add_i32 m0, s58, 0x2000
	s_add_u32 s58, s34, 0x20000
	s_addc_u32 s59, s35, 0
	s_add_i32 s60, s50, s4
	global_load_lds_dwordx4 v134, s[34:35]
	s_mov_b32 m0, s60
	s_nop 0
	global_load_lds_dwordx4 v130, s[58:59]
	s_add_i32 m0, s60, 0x2000
	s_nop 0
	global_load_lds_dwordx4 v134, s[58:59]
	s_waitcnt vmcnt(6) lgkmcnt(0)
	s_barrier
	s_setprio 1
	v_mfma_f32_16x16x32_bf16 v[60:63], v[144:147], v[182:185], v[60:63]
	v_mfma_f32_16x16x32_bf16 v[56:59], v[158:161], v[182:185], v[56:59]
	v_mfma_f32_16x16x32_bf16 v[44:47], v[144:147], v[190:193], v[44:47]
	v_mfma_f32_16x16x32_bf16 v[40:43], v[158:161], v[190:193], v[40:43]
	v_mfma_f32_16x16x32_bf16 v[28:31], v[144:147], v[198:201], v[28:31]
	v_mfma_f32_16x16x32_bf16 v[24:27], v[158:161], v[198:201], v[24:27]
	v_mfma_f32_16x16x32_bf16 v[12:15], v[144:147], v[206:209], v[12:15]
	v_mfma_f32_16x16x32_bf16 v[8:11], v[158:161], v[206:209], v[8:11]
	v_mfma_f32_16x16x32_bf16 v[60:63], v[154:157], v[186:189], v[60:63]
	v_mfma_f32_16x16x32_bf16 v[56:59], v[162:165], v[186:189], v[56:59]
	v_mfma_f32_16x16x32_bf16 v[44:47], v[154:157], v[194:197], v[44:47]
	v_mfma_f32_16x16x32_bf16 v[40:43], v[162:165], v[194:197], v[40:43]
	v_mfma_f32_16x16x32_bf16 v[28:31], v[154:157], v[202:205], v[28:31]
	v_mfma_f32_16x16x32_bf16 v[24:27], v[162:165], v[202:205], v[24:27]
	v_mfma_f32_16x16x32_bf16 v[12:15], v[154:157], v[210:213], v[12:15]
	v_mfma_f32_16x16x32_bf16 v[8:11], v[162:165], v[210:213], v[8:11]
	s_setprio 0
	s_setprio 1
	v_mfma_f32_16x16x32_bf16 v[52:55], v[166:169], v[182:185], v[52:55]
	v_mfma_f32_16x16x32_bf16 v[48:51], v[174:177], v[182:185], v[48:51]
	v_mfma_f32_16x16x32_bf16 v[36:39], v[166:169], v[190:193], v[36:39]
	v_mfma_f32_16x16x32_bf16 v[32:35], v[174:177], v[190:193], v[32:35]
	v_mfma_f32_16x16x32_bf16 v[20:23], v[166:169], v[198:201], v[20:23]
	v_mfma_f32_16x16x32_bf16 v[16:19], v[174:177], v[198:201], v[16:19]
	v_mfma_f32_16x16x32_bf16 v[4:7], v[166:169], v[206:209], v[4:7]
	v_mfma_f32_16x16x32_bf16 v[0:3], v[174:177], v[206:209], v[0:3]
	v_mfma_f32_16x16x32_bf16 v[52:55], v[170:173], v[186:189], v[52:55]
	v_mfma_f32_16x16x32_bf16 v[48:51], v[178:181], v[186:189], v[48:51]
	v_mfma_f32_16x16x32_bf16 v[36:39], v[170:173], v[194:197], v[36:39]
	v_mfma_f32_16x16x32_bf16 v[32:35], v[178:181], v[194:197], v[32:35]
	v_mfma_f32_16x16x32_bf16 v[20:23], v[170:173], v[202:205], v[20:23]
	v_mfma_f32_16x16x32_bf16 v[16:19], v[178:181], v[202:205], v[16:19]
	v_mfma_f32_16x16x32_bf16 v[4:7], v[170:173], v[210:213], v[4:7]
	v_mfma_f32_16x16x32_bf16 v[0:3], v[178:181], v[210:213], v[0:3]
	s_setprio 0
	s_barrier
; #define PG8_STAGE(bufoff, gbase, voff) do { _Pragma("unroll") for (int _i = 0; _i < 2; ++_i) \
;         __builtin_amdgcn_global_load_lds((const unsigned*)((const char*)(gbase) + (voff)[_i]), (PG8_LAS unsigned*)(lds + (bufoff) + ldsw + _i * 8192), 16, 0, 0); } while (0)
; #define PG8_LDA(dst, b, h) do { _Pragma("unroll") for (int m = 0; m < 4; ++m) _Pragma("unroll") for (int k = 0; k < 2; ++k) dst[m][k] = *(const PG8_LAS bf16x8*)(lds + PG8_SA(b, h) + aoff + m * 2048 + k * 1024); } while (0)
; #define PG8_WAIT_V(n) asm volatile("s_waitcnt vmcnt(" #n ")" ::: "memory")
; #define PG8_BAR __builtin_amdgcn_s_barrier()
; template <class Epi, class Sched, bool ALIGN_EPI = false, bool SP2 = false>
; __device__ __forceinline__ void gemm_phase(PG8_LAS unsigned char* lds, const Gemm g, const Sched& S, const Epi& E) {
;     ...
;         for (int t = 0; t < nt; t += 2) {
;             const bool last = (t == nt - 2);
;             if constexpr (Epi::HAS_MID) { if (t == E.mid_t) E.mid(acc, cur, wr, wc, fr, fq); }
;             const char* a1 = cA + (size_t)(t + 1) * kstep;
;             const char* a2 = last ? nA : cA + (size_t)(t + 2) * kstep; const char* b2 = last ? nB : cB + (size_t)(t + 2) * kstep;
;             const char* a3 = a2 + kstep; const char* b3 = b2 + kstep;
;             if (last && has_next) S.a_ready(nxt);
;             if constexpr (SP2) {
;             PG8_LDB(B0, 0, 0); PG8_LDB(B1, 0, 1); PG8_SCHED; PG8_LDA(At, 0, 0); PG8_STAGE(PG8_SA(1, 1), a1 + hstepA, voffA);
;             PG8_WAIT_V(8); PG8_WAIT_L(0); PG8_BAR; PG8_MMA(0, 0, At, B0); PG8_MMA(0, 1, At, B1); PG8_BAR; PG8_SCHED;
;             PG8_LDA(At, 0, 1); PG8_STAGE(PG8_SB(0, 0), b2, voffB); PG8_STAGE(PG8_SB(0, 1), b2 + hstepB, voffB); PG8_STAGE(PG8_SA(0, 0), a2, voffA);
;             PG8_WAIT_V(8); PG8_WAIT_L(0); PG8_BAR; PG8_MMA(1, 0, At, B0); PG8_MMA(1, 1, At, B1); PG8_BAR; PG8_SCHED;
;             PG8_LDB(B0, 1, 0); PG8_LDB(B1, 1, 1); PG8_SCHED; PG8_LDA(At, 1, 0); PG8_STAGE(PG8_SA(0, 1), a2 + hstepA, voffA);
;             PG8_WAIT_V(8); PG8_WAIT_L(0); PG8_BAR; PG8_MMA(0, 0, At, B0); PG8_MMA(0, 1, At, B1); PG8_BAR; PG8_SCHED;
;             PG8_LDA(At, 1, 1); PG8_STAGE(PG8_SB(1, 0), b3, voffB); PG8_STAGE(PG8_SB(1, 1), b3 + hstepB, voffB); PG8_STAGE(PG8_SA(1, 0), a3, voffA);
;             PG8_WAIT_V(8); PG8_WAIT_L(0); PG8_BAR; PG8_MMA(1, 0, At, B0); PG8_MMA(1, 1, At, B1); PG8_BAR; PG8_SCHED;
	s_add_i32 s58, 0, 0x18000
	s_add_i32 s59, 0, 0x1c000
	v_add_u32_e32 v162, s58, v150
	v_add_u32_e32 v178, s59, v150
	ds_read_b128 v[144:147], v162
	ds_read_b128 v[154:157], v162 offset:1024
	ds_read_b128 v[158:161], v162 offset:2048
	ds_read_b128 v[162:165], v162 offset:3072
	ds_read_b128 v[166:169], v178
	ds_read_b128 v[170:173], v178 offset:1024
	ds_read_b128 v[174:177], v178 offset:2048
	ds_read_b128 v[178:181], v178 offset:3072
	s_mov_b64 s[100:101], s[38:39]
	s_add_u32 s38, s38, 0x20000
	s_addc_u32 s39, s39, 0
	ds_read_b128 v[182:185], v153 offset:32768
	ds_read_b128 v[186:189], v153 offset:33792
	ds_read_b128 v[190:193], v153 offset:34816
	ds_read_b128 v[194:197], v153 offset:35840
	ds_read_b128 v[198:201], v153 offset:36864
	ds_read_b128 v[202:205], v153 offset:37888
	ds_read_b128 v[206:209], v153 offset:38912
	ds_read_b128 v[210:213], v153 offset:39936
	s_mov_b32 m0, s5
	s_nop 0
	global_load_lds_dwordx4 v128, s[100:101]
	s_mov_b32 m0, s6
	s_nop 0
	global_load_lds_dwordx4 v132, s[100:101]
	s_mov_b32 m0, s7
	s_nop 0
	global_load_lds_dwordx4 v128, s[38:39]
	s_mov_b32 m0, s33
	s_nop 0
	global_load_lds_dwordx4 v132, s[38:39]
	s_waitcnt vmcnt(8) lgkmcnt(0)
	s_barrier
	s_setprio 1
	v_mfma_f32_16x16x32_bf16 v[124:127], v[144:147], v[182:185], v[124:127]
	v_mfma_f32_16x16x32_bf16 v[120:123], v[158:161], v[182:185], v[120:123]
	v_mfma_f32_16x16x32_bf16 v[108:111], v[144:147], v[190:193], v[108:111]
	v_mfma_f32_16x16x32_bf16 v[104:107], v[158:161], v[190:193], v[104:107]
	v_mfma_f32_16x16x32_bf16 v[92:95], v[144:147], v[198:201], v[92:95]
	v_mfma_f32_16x16x32_bf16 v[88:91], v[158:161], v[198:201], v[88:91]
	v_mfma_f32_16x16x32_bf16 v[76:79], v[144:147], v[206:209], v[76:79]
	v_mfma_f32_16x16x32_bf16 v[72:75], v[158:161], v[206:209], v[72:75]
	v_mfma_f32_16x16x32_bf16 v[124:127], v[154:157], v[186:189], v[124:127]
	v_mfma_f32_16x16x32_bf16 v[120:123], v[162:165], v[186:189], v[120:123]
	v_mfma_f32_16x16x32_bf16 v[108:111], v[154:157], v[194:197], v[108:111]
	v_mfma_f32_16x16x32_bf16 v[104:107], v[162:165], v[194:197], v[104:107]
	v_mfma_f32_16x16x32_bf16 v[92:95], v[154:157], v[202:205], v[92:95]
	v_mfma_f32_16x16x32_bf16 v[88:91], v[162:165], v[202:205], v[88:91]
	v_mfma_f32_16x16x32_bf16 v[76:79], v[154:157], v[210:213], v[76:79]
	v_mfma_f32_16x16x32_bf16 v[72:75], v[162:165], v[210:213], v[72:75]
	s_setprio 0
	s_setprio 1
	v_mfma_f32_16x16x32_bf16 v[116:119], v[166:169], v[182:185], v[116:119]
	v_mfma_f32_16x16x32_bf16 v[112:115], v[174:177], v[182:185], v[112:115]
	v_mfma_f32_16x16x32_bf16 v[100:103], v[166:169], v[190:193], v[100:103]
	v_mfma_f32_16x16x32_bf16 v[96:99], v[174:177], v[190:193], v[96:99]
	v_mfma_f32_16x16x32_bf16 v[84:87], v[166:169], v[198:201], v[84:87]
	v_mfma_f32_16x16x32_bf16 v[80:83], v[174:177], v[198:201], v[80:83]
	v_mfma_f32_16x16x32_bf16 v[68:71], v[166:169], v[206:209], v[68:71]
	v_mfma_f32_16x16x32_bf16 v[64:67], v[174:177], v[206:209], v[64:67]
	v_mfma_f32_16x16x32_bf16 v[116:119], v[170:173], v[186:189], v[116:119]
	v_mfma_f32_16x16x32_bf16 v[112:115], v[178:181], v[186:189], v[112:115]
	v_mfma_f32_16x16x32_bf16 v[100:103], v[170:173], v[194:197], v[100:103]
	v_mfma_f32_16x16x32_bf16 v[96:99], v[178:181], v[194:197], v[96:99]
	v_mfma_f32_16x16x32_bf16 v[84:87], v[170:173], v[202:205], v[84:87]
	v_mfma_f32_16x16x32_bf16 v[80:83], v[178:181], v[202:205], v[80:83]
	v_mfma_f32_16x16x32_bf16 v[68:71], v[170:173], v[210:213], v[68:71]
	v_mfma_f32_16x16x32_bf16 v[64:67], v[178:181], v[210:213], v[64:67]
	s_setprio 0
	s_barrier
	s_add_i32 s38, s58, s4
	s_add_u32 s98, s34, 0x80
	s_addc_u32 s99, s35, 0
	s_mov_b32 m0, s38
	ds_read_b128 v[182:185], v153 offset:49152
	ds_read_b128 v[186:189], v153 offset:50176
	ds_read_b128 v[190:193], v153 offset:51200
	ds_read_b128 v[194:197], v153 offset:52224
	ds_read_b128 v[198:201], v153 offset:53248
	ds_read_b128 v[202:205], v153 offset:54272
	ds_read_b128 v[206:209], v153 offset:55296
	ds_read_b128 v[210:213], v153 offset:56320
	global_load_lds_dwordx4 v130, s[98:99]
	s_add_i32 m0, s38, 0x2000
	s_add_u32 s34, s34, 0x20080
	s_addc_u32 s35, s35, 0
	s_add_i32 s38, s59, s4
	global_load_lds_dwordx4 v134, s[98:99]
	s_mov_b32 m0, s38
	s_nop 0
	global_load_lds_dwordx4 v130, s[34:35]
	s_add_i32 m0, s38, 0x2000
	s_nop 0
	global_load_lds_dwordx4 v134, s[34:35]
	s_waitcnt vmcnt(6) lgkmcnt(0)
	s_barrier
	s_setprio 1
	v_mfma_f32_16x16x32_bf16 v[60:63], v[144:147], v[182:185], v[60:63]
	v_mfma_f32_16x16x32_bf16 v[56:59], v[158:161], v[182:185], v[56:59]
	v_mfma_f32_16x16x32_bf16 v[44:47], v[144:147], v[190:193], v[44:47]
	v_mfma_f32_16x16x32_bf16 v[40:43], v[158:161], v[190:193], v[40:43]
	v_mfma_f32_16x16x32_bf16 v[28:31], v[144:147], v[198:201], v[28:31]
	v_mfma_f32_16x16x32_bf16 v[24:27], v[158:161], v[198:201], v[24:27]
	v_mfma_f32_16x16x32_bf16 v[12:15], v[144:147], v[206:209], v[12:15]
	v_mfma_f32_16x16x32_bf16 v[8:11], v[158:161], v[206:209], v[8:11]
	v_mfma_f32_16x16x32_bf16 v[60:63], v[154:157], v[186:189], v[60:63]
	v_mfma_f32_16x16x32_bf16 v[56:59], v[162:165], v[186:189], v[56:59]
	v_mfma_f32_16x16x32_bf16 v[44:47], v[154:157], v[194:197], v[44:47]
	v_mfma_f32_16x16x32_bf16 v[40:43], v[162:165], v[194:197], v[40:43]
	v_mfma_f32_16x16x32_bf16 v[28:31], v[154:157], v[202:205], v[28:31]
	v_mfma_f32_16x16x32_bf16 v[24:27], v[162:165], v[202:205], v[24:27]
	v_mfma_f32_16x16x32_bf16 v[12:15], v[154:157], v[210:213], v[12:15]
	v_mfma_f32_16x16x32_bf16 v[8:11], v[162:165], v[210:213], v[8:11]
	s_setprio 0
	s_setprio 1
	v_mfma_f32_16x16x32_bf16 v[52:55], v[166:169], v[182:185], v[52:55]
	v_mfma_f32_16x16x32_bf16 v[48:51], v[174:177], v[182:185], v[48:51]
	v_mfma_f32_16x16x32_bf16 v[36:39], v[166:169], v[190:193], v[36:39]
	v_mfma_f32_16x16x32_bf16 v[32:35], v[174:177], v[190:193], v[32:35]
	v_mfma_f32_16x16x32_bf16 v[20:23], v[166:169], v[198:201], v[20:23]
	v_mfma_f32_16x16x32_bf16 v[16:19], v[174:177], v[198:201], v[16:19]
	v_mfma_f32_16x16x32_bf16 v[4:7], v[166:169], v[206:209], v[4:7]
	v_mfma_f32_16x16x32_bf16 v[0:3], v[174:177], v[206:209], v[0:3]
	v_mfma_f32_16x16x32_bf16 v[52:55], v[170:173], v[186:189], v[52:55]
	v_mfma_f32_16x16x32_bf16 v[48:51], v[178:181], v[186:189], v[48:51]
	v_mfma_f32_16x16x32_bf16 v[36:39], v[170:173], v[194:197], v[36:39]
	v_mfma_f32_16x16x32_bf16 v[32:35], v[178:181], v[194:197], v[32:35]
	v_mfma_f32_16x16x32_bf16 v[20:23], v[170:173], v[202:205], v[20:23]
	v_mfma_f32_16x16x32_bf16 v[16:19], v[178:181], v[202:205], v[16:19]
	v_mfma_f32_16x16x32_bf16 v[4:7], v[170:173], v[210:213], v[4:7]
	v_mfma_f32_16x16x32_bf16 v[0:3], v[178:181], v[210:213], v[0:3]
	s_setprio 0
	s_barrier
	s_add_i32 s57, s57, 2
	s_add_u32 s20, s20, 0x100
	s_addc_u32 s21, s21, 0
	s_add_u32 s53, s53, 0x100
	s_addc_u32 s56, s56, 0
	s_cmp_gt_u32 s57, 5
	s_cbranch_scc0 .LBB0_1738
	s_and_b64 vcc, exec, s[22:23]
	s_cbranch_vccz .LBB0_1741
	s_barrier
